# combo11: combo8b + the cooperative-groups grid sync after P0 and the first xcd barrier also replaced by the hand-written hierarchical barrier (own census of workgroups per XCC; one L2 writeback per XC
# speedup vs baseline: 1.0129x; 1.0129x over previous
; __device__ __forceinline__ void prenorm_rows(const float* __restrict__ xin, bf16_t* __restrict__ an, float* __restrict__ rss, const float* __restrict__ modl, int coff) {
;     const int tid = opaque_tid(), lane = tid & 63, gw = blockIdx.x * 8 + (tid >> 6), NGW = GRID * 8;
; __device__ __forceinline__ void xcd_barrier_complete(unsigned* bar, unsigned x, unsigned& nloc, unsigned& nx) {
;     const unsigned G = gridDim.x * gridDim.y * gridDim.z;
;     unsigned sum, cnt, mine, sp = 0u;
;     for (;;) {
;         sum = 0u; cnt = 0u; mine = 0u;
; #pragma unroll
;         for (unsigned j = 0; j < 16; ++j) { const unsigned c = xb_ld(&bar[XB_XCNT(j)]); sum += c; cnt += (c > 0u) ? 1u : 0u; mine = (j == x) ? c : mine; }
;         if (sum == G) break;
;         __builtin_amdgcn_s_sleep(1);
;         if ((++sp & 255u) == 0u) { if (xb_ld(&bar[XB_TMO])) break; if (sp > XB_SPIN_CAP) { atomicAdd(&bar[XB_TMO], 1u); break; } }
;     }
;     nloc = mine > 0u ? mine : 1u; nx = cnt > 0u ? cnt : 1u;
; }
; __device__ __forceinline__ void xcd_barrier(const XcdBarrier& b) {
;     asm volatile("s_waitcnt vmcnt(0)" ::: "memory");
;     __syncthreads();
;     if (threadIdx.x == 0) {
;         unsigned* bar = b.bar; unsigned bx = b.x; asm volatile("" : "+s"(bx));
;         __builtin_amdgcn_s_waitcnt(0);
;         unsigned nloc = b.st[0], nx = b.st[1];
;         if (nloc == 0u) { xcd_barrier_complete(bar, bx, nloc, nx); b.st[0] = nloc; b.st[1] = nx; }
;         const unsigned old = xb_add(&bar[XB_XSUB(bx)], 1u);
;         const unsigned gen = old / nloc;
;         if (old + 1u == (gen + 1u) * nloc) {
;             __builtin_amdgcn_fence(__ATOMIC_RELEASE, "agent");
;             asm volatile("s_waitcnt vmcnt(0)" ::: "memory");
;             const unsigned og = xb_add(&bar[XB_TOP], 1u);
;             const unsigned tg = og / nx;
;             if (og + 1u == (tg + 1u) * nx) xb_add(&bar[XB_TOPGEN], 1u);
;             else XB_SPIN(xb_ld(&bar[XB_TOPGEN]) == tg, bar);
;             __builtin_amdgcn_fence(__ATOMIC_ACQUIRE, "agent");
;             xb_add(&bar[XB_XGEN(bx)], 1u);
;             asm volatile("s_waitcnt vmcnt(0)" ::: "memory");
;         } else {
;             XB_SPIN(xb_ld(&bar[XB_XGEN(bx)]) == gen, bar);
;             __builtin_amdgcn_fence(__ATOMIC_ACQUIRE, "agent");
;             asm volatile("s_waitcnt vmcnt(0)" ::: "memory");
;         }
;     }
;     __syncthreads();
.LBB0_104:
	v_lshrrev_b32_e32 v1, 20, v0
	v_lshrrev_b32_e32 v0, 10, v0
	v_or_b32_e32 v0, v0, v1
	s_movk_i32 s2, 0x3ff
	v_and_or_b32 v0, v0, s2, v190
	v_cmp_eq_u32_e32 vcc, 0, v0
	s_waitcnt vmcnt(0) lgkmcnt(0)
	s_barrier
	s_and_saveexec_b64 s[2:3], vcc
	s_cbranch_execz .LBB0_114
	s_waitcnt vmcnt(0) lgkmcnt(0)
	v_readlane_b32 s22, v252, 0
	v_readlane_b32 s23, v252, 1
	v_readlane_b32 s12, v252, 2
	s_add_u32 s14, s22, 0x400
	s_addc_u32 s15, s23, 0
	s_mov_b64 s[24:25], exec
	s_mov_b64 exec, 0xffff
	v_mbcnt_lo_u32_b32 v19, -1, 0
	v_lshlrev_b32_e32 v19, 8, v19
	s_mov_b32 s26, 0
.Lcen_spin:
	global_load_dword v20, v19, s[14:15] sc1
	s_mov_b32 s27, 0
	s_waitcnt vmcnt(0)
	v_readlane_b32 s16, v20, 0
	s_add_i32 s27, s27, s16
	v_readlane_b32 s16, v20, 1
	s_add_i32 s27, s27, s16
	v_readlane_b32 s16, v20, 2
	s_add_i32 s27, s27, s16
	v_readlane_b32 s16, v20, 3
	s_add_i32 s27, s27, s16
	v_readlane_b32 s16, v20, 4
	s_add_i32 s27, s27, s16
	v_readlane_b32 s16, v20, 5
	s_add_i32 s27, s27, s16
	v_readlane_b32 s16, v20, 6
	s_add_i32 s27, s27, s16
	v_readlane_b32 s16, v20, 7
	s_add_i32 s27, s27, s16
	v_readlane_b32 s16, v20, 8
	s_add_i32 s27, s27, s16
	v_readlane_b32 s16, v20, 9
	s_add_i32 s27, s27, s16
	v_readlane_b32 s16, v20, 10
	s_add_i32 s27, s27, s16
	v_readlane_b32 s16, v20, 11
	s_add_i32 s27, s27, s16
	v_readlane_b32 s16, v20, 12
	s_add_i32 s27, s27, s16
	v_readlane_b32 s16, v20, 13
	s_add_i32 s27, s27, s16
	v_readlane_b32 s16, v20, 14
	s_add_i32 s27, s27, s16
	v_readlane_b32 s16, v20, 15
	s_add_i32 s27, s27, s16
	s_cmp_eq_u32 s27, 0x100
	s_cbranch_scc1 .Lcen_done
	s_sleep 1
	s_add_i32 s26, s26, 1
	s_cmp_lt_u32 s26, 0x40000
	s_cbranch_scc1 .Lcen_spin
.Lcen_done:
	v_cmp_ne_u32_e32 vcc, 0, v20
	s_bcnt1_i32_b64 s19, vcc
	s_nop 3
	v_readlane_b32 s18, v20, s12
	s_mov_b64 exec, s[24:25]
	v_mov_b32_e32 v18, 0
	v_mov_b32_e32 v0, 0x26800
	v_mov_b32_e32 v2, s18
	v_mov_b32_e32 v3, s19
	ds_write_b32 v0, v2
	ds_write_b32 v0, v3 offset:4
	s_waitcnt lgkmcnt(0)
	s_waitcnt vmcnt(0) lgkmcnt(0)
	v_mov_b32_e32 v0, 0x26800
	ds_read_b32 v2, v0
	ds_read_b32 v3, v0 offset:4
	ds_read_b32 v8, v0 offset:8
	v_readlane_b32 s22, v252, 0
	v_readlane_b32 s23, v252, 1
	v_readlane_b32 s12, v252, 2
	s_lshl_b32 s12, s12, 8
	s_add_u32 s14, s22, s12
	s_addc_u32 s15, s23, 0
	s_add_u32 s14, s14, 0x1400
	s_addc_u32 s15, s15, 0
	s_add_u32 s16, s22, 0x3400
	s_addc_u32 s17, s23, 0
	v_mov_b32_e32 v4, 1
	global_atomic_add v16, v18, v4, s[14:15] sc0
	s_waitcnt lgkmcnt(0)
	v_readfirstlane_b32 s18, v2
	v_readfirstlane_b32 s19, v3
	v_cvt_f32_u32_e32 v17, v2
	v_rcp_f32_e32 v17, v17
	s_waitcnt vmcnt(0)
	v_readfirstlane_b32 s13, v16
	v_cvt_f32_u32_e32 v6, v16
	v_mul_f32_e32 v6, v6, v17
	v_cvt_u32_f32_e32 v6, v6
	s_nop 0
	v_readfirstlane_b32 s20, v6
	s_mul_i32 s21, s20, s18
	s_cmp_gt_u32 s21, s13
	s_cbranch_scc0 .Lxbg_a
	s_sub_i32 s20, s20, 1
	s_sub_i32 s21, s21, s18
.Lxbg_a:
	s_add_i32 s21, s21, s18
	s_cmp_le_u32 s21, s13
	s_cbranch_scc0 .Lxbg_b
	s_add_i32 s20, s20, 1
	s_add_i32 s21, s21, s18
.Lxbg_b:
	s_add_i32 s13, s13, 1
	s_cmp_eq_u32 s13, s21
	s_cbranch_scc0 .Lxbg_poll
	buffer_wbl2 sc1
	s_waitcnt vmcnt(0)
	global_atomic_add v18, v4, s[16:17]
.Lxbg_poll:
	v_readfirstlane_b32 s20, v8
	s_add_i32 s20, s20, 1
	s_mul_i32 s20, s20, s19
	v_add_u32_e32 v8, 1, v8
	ds_write_b32 v0, v8 offset:8
	s_mov_b32 s21, 0
.Lxbg_spin:
	global_load_dword v16, v18, s[16:17] sc1
	s_waitcnt vmcnt(0)
	v_readfirstlane_b32 s12, v16
	s_cmp_ge_u32 s12, s20
	s_cbranch_scc1 .Lxbg_go
	s_sleep 1
	s_add_i32 s21, s21, 1
	s_cmp_lt_u32 s21, 0x40000
	s_cbranch_scc1 .Lxbg_spin
.Lxbg_go:
	buffer_inv sc1
	s_waitcnt vmcnt(0) lgkmcnt(0)
.LBB0_114:
	s_or_b64 exec, exec, s[2:3]
	v_mov_b32_e32 v0, v190
	s_barrier
	v_readlane_b32 s2, v252, 6
	v_ashrrev_i32_e32 v1, 6, v0
	s_nop 0
	v_add_u32_e32 v16, s2, v1
	s_mov_b32 s2, 0x8000
	v_cmp_gt_i32_e32 vcc, s2, v16
	s_and_saveexec_b64 s[6:7], vcc
	s_cbranch_execz .LBB0_119
	v_and_b32_e32 v1, 63, v0
	v_mbcnt_hi_u32_b32 v0, -1, v42
	v_and_b32_e32 v2, 64, v0
	v_add_u32_e32 v2, 64, v2
	v_xor_b32_e32 v3, 1, v0
	v_cmp_lt_i32_e32 vcc, v3, v2
	v_ashrrev_i32_e32 v17, 31, v16
	v_mov_b64_e32 v[8:9], 0x1f000000
	v_cndmask_b32_e32 v3, v0, v3, vcc
	v_lshlrev_b32_e32 v32, 2, v3
	v_xor_b32_e32 v3, 2, v0
	v_cmp_lt_i32_e32 vcc, v3, v2
	v_lshl_add_u64 v[20:21], v[16:17], 2, v[8:9]
	v_lshlrev_b64 v[8:9], 12, v[16:17]
	v_cndmask_b32_e32 v3, v0, v3, vcc
	v_lshlrev_b32_e32 v33, 2, v3
	v_xor_b32_e32 v3, 4, v0
	v_cmp_lt_i32_e32 vcc, v3, v2
	v_mov_b32_e32 v19, 0
	v_lshlrev_b64 v[22:23], 11, v[16:17]
	v_cndmask_b32_e32 v3, v0, v3, vcc
	v_lshlrev_b32_e32 v34, 2, v3
	v_xor_b32_e32 v3, 8, v0
	v_cmp_lt_i32_e32 vcc, v3, v2
	v_lshl_or_b32 v8, v1, 4, v8
	v_lshl_or_b32 v22, v1, 3, v22
	v_cndmask_b32_e32 v3, v0, v3, vcc
	v_lshlrev_b32_e32 v35, 2, v3
	v_xor_b32_e32 v3, 16, v0
	v_cmp_lt_i32_e32 vcc, v3, v2
	v_lshl_add_u64 v[24:25], s[68:69], 0, v[8:9]
	s_mov_b64 s[8:9], 0
	v_cndmask_b32_e32 v3, v0, v3, vcc
	v_lshlrev_b32_e32 v36, 2, v3
	v_xor_b32_e32 v3, 32, v0
	v_cmp_lt_i32_e32 vcc, v3, v2
	s_mov_b64 s[12:13], 0x1000
	s_mov_b32 s20, 0x3700000
	v_cndmask_b32_e32 v0, v0, v3, vcc
	v_lshlrev_b32_e32 v37, 2, v0
	v_lshlrev_b32_e32 v0, 2, v1
	v_or_b32_e32 v2, 0x100, v0
	v_or_b32_e32 v4, 0x200, v0
	v_or_b32_e32 v6, 0x300, v0
	v_cmp_eq_u32_e32 vcc, 0, v1
	v_lshlrev_b32_e32 v26, 2, v0
	v_lshlrev_b32_e32 v28, 2, v2
	v_lshlrev_b32_e32 v18, 2, v4
	v_lshlrev_b32_e32 v30, 2, v6
	s_mov_b64 s[14:15], 0x2000
	s_mov_b64 s[16:17], 0x400000
	s_mov_b64 s[18:19], 0x800000
	s_movk_i32 s21, 0x77ff
	v_mov_b32_e32 v27, v19
	v_mov_b32_e32 v29, v19
	s_branch .LBB0_117

; __device__ __forceinline__ unsigned xb_ld(unsigned* p)              { return __hip_atomic_load(p, __ATOMIC_RELAXED, __HIP_MEMORY_SCOPE_AGENT); }
; __device__ __forceinline__ unsigned xb_add(unsigned* p, unsigned v) { return __hip_atomic_fetch_add(p, v, __ATOMIC_RELAXED, __HIP_MEMORY_SCOPE_AGENT); }
; #define XB_SPIN(cond, bar) do { unsigned _sp = 0; while (cond) { __builtin_amdgcn_s_sleep(1); \
;     if ((++_sp & 255u) == 0u) { if (xb_ld(&(bar)[XB_TMO])) break; if (_sp > XB_SPIN_CAP) { atomicAdd(&(bar)[XB_TMO], 1u); break; } } } } while (0)
; __device__ __forceinline__ void xcd_barrier(const XcdBarrier& b) {
;     asm volatile("s_waitcnt vmcnt(0)" ::: "memory");
;     __syncthreads();
;     if (threadIdx.x == 0) {
;         unsigned* bar = b.bar; unsigned bx = b.x; asm volatile("" : "+s"(bx));
;         __builtin_amdgcn_s_waitcnt(0);
;         unsigned nloc = b.st[0], nx = b.st[1];
;         if (nloc == 0u) { xcd_barrier_complete(bar, bx, nloc, nx); b.st[0] = nloc; b.st[1] = nx; }
;         const unsigned old = xb_add(&bar[XB_XSUB(bx)], 1u);
;         const unsigned gen = old / nloc;
;         if (old + 1u == (gen + 1u) * nloc) {
;             __builtin_amdgcn_fence(__ATOMIC_RELEASE, "agent");
;             asm volatile("s_waitcnt vmcnt(0)" ::: "memory");
;             const unsigned og = xb_add(&bar[XB_TOP], 1u);
;             const unsigned tg = og / nx;
;             if (og + 1u == (tg + 1u) * nx) xb_add(&bar[XB_TOPGEN], 1u);
;             else XB_SPIN(xb_ld(&bar[XB_TOPGEN]) == tg, bar);
.LBB0_143:
	s_waitcnt vmcnt(0)
	s_waitcnt lgkmcnt(0)
	s_barrier
	s_mov_b64 s[2:3], exec
	v_readlane_b32 s4, v252, 3
	v_readlane_b32 s5, v252, 4
	s_and_b64 s[4:5], s[2:3], s[4:5]
	s_mov_b64 exec, s[4:5]
	s_cbranch_execz .LBB0_195
	v_mov_b32_e32 v10, 0
	s_waitcnt vmcnt(0) lgkmcnt(0)
	v_mov_b32_e32 v0, 0x26800
	ds_read_b32 v2, v0
	ds_read_b32 v3, v0 offset:4
	ds_read_b32 v8, v0 offset:8
	v_readlane_b32 s22, v252, 0
	v_readlane_b32 s23, v252, 1
	v_readlane_b32 s12, v252, 2
	s_lshl_b32 s12, s12, 8
	s_add_u32 s14, s22, s12
	s_addc_u32 s15, s23, 0
	s_add_u32 s14, s14, 0x1400
	s_addc_u32 s15, s15, 0
	s_add_u32 s16, s22, 0x3400
	s_addc_u32 s17, s23, 0
	v_mov_b32_e32 v4, 1
	global_atomic_add v5, v10, v4, s[14:15] sc0
	s_waitcnt lgkmcnt(0)
	v_readfirstlane_b32 s18, v2
	v_readfirstlane_b32 s19, v3
	v_cvt_f32_u32_e32 v7, v2
	v_rcp_f32_e32 v7, v7
	s_waitcnt vmcnt(0)
	v_readfirstlane_b32 s13, v5
	v_cvt_f32_u32_e32 v6, v5
	v_mul_f32_e32 v6, v6, v7
	v_cvt_u32_f32_e32 v6, v6
	s_nop 0
	v_readfirstlane_b32 s20, v6
	s_mul_i32 s21, s20, s18
	s_cmp_gt_u32 s21, s13
	s_cbranch_scc0 .Lxbr_a
	s_sub_i32 s20, s20, 1
	s_sub_i32 s21, s21, s18

; __device__ __forceinline__ unsigned xb_ld(unsigned* p)              { return __hip_atomic_load(p, __ATOMIC_RELAXED, __HIP_MEMORY_SCOPE_AGENT); }
; __device__ __forceinline__ unsigned xb_add(unsigned* p, unsigned v) { return __hip_atomic_fetch_add(p, v, __ATOMIC_RELAXED, __HIP_MEMORY_SCOPE_AGENT); }
; #define XB_SPIN(cond, bar) do { unsigned _sp = 0; while (cond) { __builtin_amdgcn_s_sleep(1); \
;     if ((++_sp & 255u) == 0u) { if (xb_ld(&(bar)[XB_TMO])) break; if (_sp > XB_SPIN_CAP) { atomicAdd(&(bar)[XB_TMO], 1u); break; } } } } while (0)
; __device__ __forceinline__ void xcd_barrier(const XcdBarrier& b) {
;     ...
;         const unsigned old = xb_add(&bar[XB_XSUB(bx)], 1u);
;         const unsigned gen = old / nloc;
;         if (old + 1u == (gen + 1u) * nloc) {
;             __builtin_amdgcn_fence(__ATOMIC_RELEASE, "agent");
;             asm volatile("s_waitcnt vmcnt(0)" ::: "memory");
;             const unsigned og = xb_add(&bar[XB_TOP], 1u);
;             const unsigned tg = og / nx;
;             if (og + 1u == (tg + 1u) * nx) xb_add(&bar[XB_TOPGEN], 1u);
;             else XB_SPIN(xb_ld(&bar[XB_TOPGEN]) == tg, bar);
.Lxbr_b:
	s_add_i32 s13, s13, 1
	s_cmp_eq_u32 s13, s21
	s_cbranch_scc0 .Lxbr_poll
	buffer_wbl2 sc1
	s_waitcnt vmcnt(0)
	global_atomic_add v10, v4, s[16:17]

; __device__ __forceinline__ unsigned xb_ld(unsigned* p)              { return __hip_atomic_load(p, __ATOMIC_RELAXED, __HIP_MEMORY_SCOPE_AGENT); }
; __device__ __forceinline__ unsigned xb_add(unsigned* p, unsigned v) { return __hip_atomic_fetch_add(p, v, __ATOMIC_RELAXED, __HIP_MEMORY_SCOPE_AGENT); }
; #define XB_SPIN(cond, bar) do { unsigned _sp = 0; while (cond) { __builtin_amdgcn_s_sleep(1); \
;     if ((++_sp & 255u) == 0u) { if (xb_ld(&(bar)[XB_TMO])) break; if (_sp > XB_SPIN_CAP) { atomicAdd(&(bar)[XB_TMO], 1u); break; } } } } while (0)
; __device__ __forceinline__ void xcd_barrier(const XcdBarrier& b) {
;     ...
;             else XB_SPIN(xb_ld(&bar[XB_TOPGEN]) == tg, bar);
;             __builtin_amdgcn_fence(__ATOMIC_ACQUIRE, "agent");
;             xb_add(&bar[XB_XGEN(bx)], 1u);
;             asm volatile("s_waitcnt vmcnt(0)" ::: "memory");
;         } else {
;             XB_SPIN(xb_ld(&bar[XB_XGEN(bx)]) == gen, bar);
;             __builtin_amdgcn_fence(__ATOMIC_ACQUIRE, "agent");
;             asm volatile("s_waitcnt vmcnt(0)" ::: "memory");
;         }
;     }
;     __syncthreads();
; __global__ void __launch_bounds__(512, 2) mega_fwd(Args a) {
;     ...
;     unsigned char* ws = a.ws;
;     const float* x_in = a.in[0]; const float* c_in = a.in[1]; const int* pos = (const int*)a.in[2];
;     const float* w_ada = a.in[3]; const float* b_ada = a.in[4];
;     float* mod = (float*)(ws + WS_MOD); float* cosT = (float*)(ws + WS_COS); float* sinT = (float*)(ws + WS_SIN);
;     bf16_t* HN = (bf16_t*)(ws + WS_HN); bf16_t* QN = (bf16_t*)(ws + WS_QN); bf16_t* KVN = (bf16_t*)(ws + WS_KVN);
;     float* GST = (float*)(ws + WS_GST); float* GDV = (float*)(ws + WS_GDV); float* BT = (float*)(ws + WS_BT);
;     bf16_t* PROJ = (bf16_t*)(ws + WS_R + R_PROJ); bf16_t* QB_ = (bf16_t*)(ws + WS_R + R_Q); bf16_t* KB_ = (bf16_t*)(ws + WS_R + R_K); bf16_t* VB_ = (bf16_t*)(ws + WS_R + R_V);
;     bf16_t* HB = (bf16_t*)(ws + WS_R);
;     float* xout = a.out;
;     float* RSS = (float*)(ws + WS_RSS); float* BIAS = (float*)(ws + WS_BIAS); bf16_t* AN1 = (bf16_t*)(ws + WS_GST);
.Lxbr_spin:
	global_load_dword v5, v10, s[16:17] sc1
	s_waitcnt vmcnt(0)
	v_readfirstlane_b32 s12, v5
	s_cmp_ge_u32 s12, s20
	s_cbranch_scc1 .Lxbr_go
	s_sleep 1
	s_add_i32 s21, s21, 1
	s_cmp_lt_u32 s21, 0x40000
	s_cbranch_scc1 .Lxbr_spin
.Lxbr_go:
	buffer_inv sc1
	s_waitcnt vmcnt(0) lgkmcnt(0)
.LBB0_195:
	v_writelane_b32 v252, s76, 7
	s_nop 1
	v_writelane_b32 v252, s77, 8
	v_writelane_b32 v252, s68, 9
	s_nop 1
	v_writelane_b32 v252, s69, 10
	v_writelane_b32 v252, s70, 11
	v_writelane_b32 v252, s71, 12
	v_writelane_b32 v252, s72, 13
	v_writelane_b32 v252, s73, 14
	v_writelane_b32 v252, s74, 15
	v_writelane_b32 v252, s75, 16
	s_or_b64 exec, exec, s[2:3]
	s_add_u32 s2, s90, 0x1f110000
	v_writelane_b32 v252, s2, 17
	s_addc_u32 s2, s91, 0
	v_writelane_b32 v252, s2, 18
	s_add_u32 s2, s90, 0x2f00000
	s_addc_u32 s3, s91, 0
	v_writelane_b32 v252, s2, 19
	s_mov_b32 s79, 0
	v_mov_b32_e32 v161, 0
	v_writelane_b32 v252, s3, 20
	s_add_u32 s2, s90, 0x3300000
	s_addc_u32 s3, s91, 0
	s_add_u32 s54, s90, 0x3700000
	v_writelane_b32 v252, s2, 21
	s_addc_u32 s55, s91, 0
	v_mov_b32_e32 v199, 0x358637bd
	v_writelane_b32 v252, s3, 22
	s_add_u32 s2, s90, 0x7700000
	s_addc_u32 s3, s91, 0
	v_writelane_b32 v252, s2, 23
	v_mov_b32_e32 v201, 0x260
	v_mov_b32_e32 v202, 0x41b17218
	v_writelane_b32 v252, s3, 24
	s_add_u32 s2, s90, 0x8700000
	s_addc_u32 s3, s91, 0
	s_add_u32 s56, s90, 0x8f00000
	v_writelane_b32 v252, s2, 25
	s_addc_u32 s57, s91, 0
	v_mov_b32_e32 v203, 0xff800000
	v_writelane_b32 v252, s3, 26
	s_add_u32 s2, s90, 0xcf00000
	s_addc_u32 s3, s91, 0
	s_add_u32 s58, s90, 0x1d000000
	s_addc_u32 s59, s91, 0
	s_add_u32 s60, s90, 0xd000000
	s_addc_u32 s61, s91, 0
	s_add_u32 s62, s90, 0x15000000
	s_addc_u32 s63, s91, 0
	s_add_u32 s64, s90, 0x18000000
	s_addc_u32 s65, s91, 0
	s_add_u32 s68, s90, 0x1b000000
	v_writelane_b32 v252, s2, 27
	s_addc_u32 s69, s91, 0
	s_movk_i32 s67, 0x180
	v_writelane_b32 v252, s3, 28
	s_add_u32 s2, s90, 0x1f000000
	v_writelane_b32 v252, s2, 29
	s_addc_u32 s2, s91, 0
	v_writelane_b32 v252, s2, 30
	s_add_u32 s2, s90, 0x1f100000
	v_writelane_b32 v252, s2, 31
	s_addc_u32 s2, s91, 0
	s_cmpk_lt_i32 s66, 0x400
	v_writelane_b32 v252, s2, 32
	s_cselect_b64 s[2:3], -1, 0
	v_writelane_b32 v252, s2, 33
	s_ashr_i32 s53, s66, 31
	s_mov_b32 s51, 0x10000
	v_writelane_b32 v252, s3, 34
	s_lshr_b32 s2, s53, 29
	s_add_i32 s3, s66, s2
	s_ashr_i32 s2, s3, 3
	s_and_b32 s3, s3, -8
	s_sub_i32 s3, s66, s3
	s_lshl_b32 s4, s3, 7
	s_cmp_eq_u64 s[90:91], 0
	s_cselect_b64 s[80:81], -1, 0
	s_cmp_lg_u64 s[90:91], 0
	s_cselect_b64 s[82:83], -1, 0
	s_add_u32 s6, s90, 0x2e80200
	s_addc_u32 s7, s91, 0
	s_add_u32 s84, s90, 0x2e80400
	s_addc_u32 s85, s91, 0
	s_add_u32 s86, s90, 0x2e80500
	s_addc_u32 s87, s91, 0
	s_add_u32 s92, s90, 0x2e80600
	s_addc_u32 s93, s91, 0
	s_add_u32 s94, s90, 0x2e80700
	s_addc_u32 s95, s91, 0
	s_add_u32 s96, s90, 0x2e80800
	v_writelane_b32 v252, s6, 35
	s_addc_u32 s97, s91, 0
	s_mov_b32 s52, 0x14000
	v_writelane_b32 v252, s7, 36
	s_add_u32 s6, s90, 0x2e80900
	s_addc_u32 s7, s91, 0
	v_writelane_b32 v252, s6, 37
	s_movk_i32 s49, 0x4000
	s_mov_b32 s22, 0x18000
	v_writelane_b32 v252, s7, 38
	s_add_u32 s6, s90, 0x2e80a00
	s_addc_u32 s7, s91, 0
	v_writelane_b32 v252, s6, 39
	s_mov_b32 s23, 0x8000
	s_mov_b32 s26, 0xbfb8aa3b
	v_writelane_b32 v252, s7, 40
	s_add_u32 s6, s90, 0x2e80b00
	s_addc_u32 s7, s91, 0
	v_writelane_b32 v252, s6, 41
	s_mov_b32 s27, 0x800000
	s_mov_b32 s28, 0x3f317217
	v_writelane_b32 v252, s7, 42
	s_add_u32 s6, s90, 0x2e80c00
	s_addc_u32 s7, s91, 0
	v_writelane_b32 v252, s6, 43
	s_mov_b32 s29, 0x7f800000
	s_mov_b32 s75, 0x5040100
	v_writelane_b32 v252, s7, 44
	s_add_u32 s6, s90, 0x2e80d00
	s_addc_u32 s7, s91, 0
	v_writelane_b32 v252, s6, 45
	s_mov_b64 s[24:25], 0x100000
	s_mov_b64 s[38:39], 0x80
	v_writelane_b32 v252, s7, 46
	s_add_u32 s6, s90, 0x2e80e00
	s_addc_u32 s7, s91, 0
	v_writelane_b32 v252, s6, 47
	s_mov_b64 s[30:31], 0x2000
	s_mov_b32 s74, 0x3dd53b94
	v_writelane_b32 v252, s7, 48
	s_add_u32 s6, s90, 0x2e80f00
	s_addc_u32 s7, s91, 0
	v_writelane_b32 v252, s6, 49
	s_waitcnt lgkmcnt(0)
	s_barrier
	v_writelane_b32 v252, s7, 50
	s_add_u32 s6, s90, 0x2e81000
	s_addc_u32 s7, s91, 0
	v_writelane_b32 v252, s6, 51
	s_nop 1
	v_writelane_b32 v252, s7, 52
	s_add_u32 s6, s90, 0x2e81100
	s_addc_u32 s7, s91, 0
	v_writelane_b32 v252, s6, 53
	s_nop 1
	v_writelane_b32 v252, s7, 54
	s_add_u32 s6, s90, 0x2e81200
	s_addc_u32 s7, s91, 0
	v_writelane_b32 v252, s6, 55
	s_nop 1
	v_writelane_b32 v252, s7, 56
	s_add_u32 s6, s90, 0x2e81300
	s_addc_u32 s7, s91, 0
	v_writelane_b32 v252, s6, 57
	s_nop 1
	v_writelane_b32 v252, s7, 58
	s_add_u32 s6, s90, 0x2e83400
	s_addc_u32 s7, s91, 0
	v_writelane_b32 v252, s6, 59
	s_nop 1
	v_writelane_b32 v252, s7, 60
	s_add_u32 s6, s90, 0x2e83500
	s_addc_u32 s7, s91, 0
	v_writelane_b32 v252, s6, 61
	s_cmpk_lt_i32 s66, 0x100
	s_nop 0
	v_writelane_b32 v252, s7, 62
	s_cselect_b64 s[6:7], -1, 0
	s_lshl_b32 s5, s3, 5
	v_writelane_b32 v252, s6, 63
	s_cmpk_lt_i32 s66, 0x80
	s_nop 0
	v_writelane_b32 v253, s7, 0
	s_cselect_b64 s[6:7], -1, 0
	v_writelane_b32 v253, s6, 1
	s_nop 1
	v_writelane_b32 v253, s7, 2
	s_lshl_b32 s6, s3, 4
	s_cmpk_lt_i32 s66, 0x200
	s_cselect_b64 s[8:9], -1, 0
	v_writelane_b32 v253, s8, 3
	s_lshl_b32 s7, s66, 7
	s_and_b32 s7, s7, 0x180
	v_writelane_b32 v253, s9, 4
	v_writelane_b32 v253, s7, 5
	s_lshl_b32 s7, s3, 6
	s_and_b32 s8, s66, 7
	s_cmpk_lt_i32 s66, 0x800
	v_writelane_b32 v253, s8, 6
	s_cselect_b64 s[8:9], -1, 0
	v_writelane_b32 v253, s8, 7
	s_nop 1
	v_writelane_b32 v253, s9, 8
	s_lshl_b32 s8, s3, 8
	s_cmp_lt_i32 s3, 0
	s_mul_i32 s9, s3, 0x81
	s_cselect_b32 s4, s9, s4
	s_mul_i32 s9, s3, 33
	s_cselect_b32 s5, s9, s5
;     __host__ __device__ bool next(int i, Unit& u) const {
;         const long L = (long)i * G + c; if (L >= nwg) return false;
;         int wgid = (int)L; { const int q = nwg / NXCD, r = nwg % NXCD, xcd = wgid % NXCD, off = wgid / NXCD; wgid = (xcd < r ? xcd * (q + 1) : r * (q + 1) + (xcd - r) * q) + off; }
;         const int nig = WGM * nN, gid = wgid / nig, fm = gid * WGM, gsz = (nM - fm) < WGM ? (nM - fm) : WGM;
;         u.pm = fm + ((wgid % nig) % gsz); u.pn = (wgid % nig) / gsz; return true;
; template <class Epi, class Sched, bool ALIGN_EPI = false, bool SP2 = false>
; __device__ __forceinline__ void gemm_phase(PG8_LAS unsigned char* lds, const Gemm g, const Sched& S, const Epi& E) {
;     ...
;     const char* cA = (const char*)g.A + (size_t)cur.pm * tstep; const char* cB = (const char*)g.Bt + (size_t)cur.pn * tstep;
	s_mul_i32 s9, s3, 17
	s_cselect_b32 s6, s9, s6
	s_mul_i32 s9, s3, 0x41
	s_mulk_i32 s3, 0x101
	s_cselect_b32 s7, s9, s7
	s_cselect_b32 s3, s3, s8
	s_add_i32 s4, s4, s2
	s_ashr_i32 s8, s4, 31
	s_lshr_b32 s8, s8, 26
	s_add_i32 s8, s4, s8
	s_and_b32 s9, s8, 0xffc0
	s_sub_i32 s4, s4, s9
	s_bfe_i32 s9, s4, 0x80000
	s_bfe_u32 s9, s9, 0x3000c
	s_add_i32 s9, s4, s9
	s_and_b32 s12, s9, 0xf8
	s_add_i32 s5, s5, s2
	s_sub_i32 s4, s4, s12
	s_ashr_i32 s12, s5, 31
	s_lshr_b32 s12, s12, 28
	s_add_i32 s12, s5, s12
	s_and_b32 s13, s12, 0xfff0
	s_sub_i32 s5, s5, s13
	s_bfe_i32 s13, s5, 0x80000
	s_bfe_u32 s13, s13, 0x3000c
	s_add_i32 s13, s5, s13
	s_and_b32 s14, s13, 0xf8
	s_sub_i32 s5, s5, s14
	s_ashr_i32 s12, s12, 4
	s_lshl_b32 s12, s12, 3
	s_sext_i32_i8 s5, s5
	s_add_i32 s15, s12, s5
	s_add_i32 s5, s7, s2
	s_ashr_i32 s7, s5, 31
	s_lshr_b32 s7, s7, 27
	s_add_i32 s16, s6, s2
	s_add_i32 s2, s3, s2
	s_add_i32 s7, s5, s7
	s_ashr_i32 s3, s2, 31
	s_and_b32 s12, s7, 0xffe0
	s_lshr_b32 s3, s3, 25
	s_sub_i32 s5, s5, s12
	s_add_i32 s3, s2, s3
	s_bfe_i32 s12, s5, 0x80000
	s_and_b32 s6, s3, 0xff80
	s_bfe_u32 s12, s12, 0x3000c
	s_sub_i32 s2, s2, s6
	s_add_i32 s12, s5, s12
	s_bfe_i32 s6, s2, 0x80000
	s_and_b32 s14, s12, 0xf8
	s_bfe_u32 s6, s6, 0x3000c
	s_sub_i32 s5, s5, s14
	s_add_i32 s6, s2, s6
	s_ashr_i32 s8, s8, 6
	s_ashr_i32 s7, s7, 5
	s_and_b32 s14, s6, 0xf8
	s_lshl_b32 s8, s8, 3
	s_sext_i32_i8 s4, s4
	s_lshl_b32 s7, s7, 3
	s_sext_i32_i8 s5, s5
	s_sub_i32 s2, s2, s14
	s_add_i32 s18, s8, s4
	s_bfe_i32 s8, s12, 0x80000
	s_add_i32 s12, s7, s5
	s_ashr_i32 s3, s3, 7
	s_bfe_i32 s5, s6, 0x80000
	s_lshl_b32 s3, s3, 3
	s_sext_i32_i16 s5, s5
	s_sext_i32_i8 s2, s2
	s_add_i32 s20, s3, s2
	s_ashr_i32 s2, s5, 3
	v_writelane_b32 v253, s2, 9
	s_lshr_b32 s2, s5, 3
	s_bfe_i64 s[2:3], s[2:3], 0x100000
	s_bfe_i32 s9, s9, 0x80000
	s_lshl_b64 s[2:3], s[2:3], 19
	s_sext_i32_i16 s9, s9
	s_bfe_i32 s4, s13, 0x80000
	v_writelane_b32 v253, s2, 10
	s_sext_i32_i16 s4, s4
	s_sext_i32_i16 s8, s8
	v_writelane_b32 v253, s3, 11
	s_ashr_i32 s2, s9, 3
	v_writelane_b32 v253, s2, 12
	s_ashr_i32 s3, s4, 3
	v_writelane_b32 v253, s3, 13
	v_writelane_b32 v253, s16, 14
	s_ashr_i32 s3, s16, 31
	v_writelane_b32 v253, s3, 15
	s_ashr_i32 s3, s8, 3
	v_writelane_b32 v253, s3, 16
	s_lshr_b32 s6, s8, 3
	s_mov_b32 s8, s20
	s_ashr_i32 s21, s20, 31
	s_lshr_b32 s2, s9, 3
	v_writelane_b32 v253, s8, 17
	s_lshr_b32 s4, s4, 3
	s_nop 0
	v_writelane_b32 v253, s9, 18
	s_lshl_b64 s[8:9], s[20:21], 19
	s_add_u32 s8, s56, s8
	s_addc_u32 s9, s57, s9
	s_add_u32 s16, s8, 0x40000
	v_writelane_b32 v253, s8, 19
	s_addc_u32 s17, s9, 0
	s_bfe_i64 s[2:3], s[2:3], 0x100000
	v_writelane_b32 v253, s9, 20
	v_writelane_b32 v253, s16, 21
	s_lshl_b64 s[2:3], s[2:3], 19
	s_ashr_i32 s19, s18, 31
	v_writelane_b32 v253, s17, 22
	v_writelane_b32 v253, s2, 23
	s_nop 1
	v_writelane_b32 v253, s3, 24
	s_mov_b32 s2, s18
	v_writelane_b32 v253, s2, 25
	s_nop 1
	v_writelane_b32 v253, s3, 26
	s_lshl_b64 s[2:3], s[18:19], 19
	s_add_u32 s2, s54, s2
	s_addc_u32 s3, s55, s3
	s_add_u32 s8, s2, 0x40000
	v_writelane_b32 v253, s2, 27
	s_addc_u32 s9, s3, 0
	s_ashr_i32 s13, s12, 31
	v_writelane_b32 v253, s3, 28
	v_writelane_b32 v253, s8, 29
	s_bfe_i64 s[2:3], s[4:5], 0x100000
	s_bfe_i64 s[4:5], s[6:7], 0x100000
	v_writelane_b32 v253, s9, 30
	v_writelane_b32 v253, s2, 31
	s_lshl_b64 s[6:7], s[4:5], 19
	s_nop 0
	v_writelane_b32 v253, s3, 32
	v_writelane_b32 v253, s15, 33
	s_ashr_i32 s2, s15, 31
	v_writelane_b32 v253, s2, 34
	s_lshl_b64 s[2:3], s[12:13], 19
	v_writelane_b32 v253, s6, 35
	s_add_u32 s2, s54, s2
	s_addc_u32 s3, s55, s3
	v_writelane_b32 v253, s7, 36
	s_add_u32 s6, s2, 0x40000
	v_writelane_b32 v253, s2, 37
	s_addc_u32 s7, s3, 0
	s_nop 0
	v_writelane_b32 v253, s3, 38
	v_writelane_b32 v253, s6, 39
	s_nop 1
	v_writelane_b32 v253, s7, 40
	v_writelane_b32 v253, s12, 41
	s_lshl_b64 s[2:3], s[12:13], 21
	s_nop 0
	v_writelane_b32 v253, s13, 42
	v_writelane_b32 v253, s4, 43
	s_nop 1
	v_writelane_b32 v253, s5, 44
	s_lshl_b64 s[4:5], s[4:5], 21
	v_writelane_b32 v253, s4, 45
	s_nop 1
	v_writelane_b32 v253, s5, 46
	s_add_u32 s4, s60, s2
	s_mul_i32 s2, s11, s10
	s_mul_i32 s2, s2, s33
	s_addc_u32 s5, s61, s3
	v_writelane_b32 v253, s2, 47
	s_add_u32 s2, s4, 0x100000
	v_writelane_b32 v253, s4, 48
	s_addc_u32 s3, s5, 0
	s_load_dwordx8 s[8:15], s[0:1], 0x30
	v_writelane_b32 v253, s5, 49
	v_writelane_b32 v253, s2, 50
	s_mov_b64 s[4:5], -1
	s_nop 0
	v_writelane_b32 v253, s3, 51
	s_lshl_b32 s2, s66, 8
	v_writelane_b32 v253, s2, 52
	s_lshl_b32 s2, s66, 5
	v_writelane_b32 v253, s2, 53
	s_add_u32 s2, s90, 0xd000240
	s_addc_u32 s3, s91, 0
	v_writelane_b32 v253, s2, 54
	s_nop 1
	v_writelane_b32 v253, s3, 55
	s_add_u32 s2, s90, 0x1d000080
	s_addc_u32 s3, s91, 0
	v_writelane_b32 v253, s2, 56
	s_nop 1
	v_writelane_b32 v253, s3, 57
	s_add_i32 s2, 0, 0x26800
	v_writelane_b32 v253, s2, 58
	s_add_i32 s2, 0, 0x26804
	v_writelane_b32 v253, s2, 59
	s_add_i32 s2, 0, 0x20200
	v_writelane_b32 v253, s2, 60
	s_add_i32 s2, 0, 0x20400
	v_writelane_b32 v253, s2, 61
	s_add_i32 s2, 0, 0x20600
	v_writelane_b32 v253, s2, 62
	s_add_i32 s2, 0, 0x21000
	v_writelane_b32 v253, s2, 63
	s_add_i32 s2, 0, 0x21200
	v_writelane_b32 v254, s2, 0
	s_add_i32 s2, 0, 0x21400
	v_writelane_b32 v254, s2, 1
	s_add_i32 s2, 0, 0x21600
	v_writelane_b32 v254, s2, 2
	s_mov_b64 s[2:3], 0
	v_writelane_b32 v254, s2, 3
	s_nop 1
	v_writelane_b32 v254, s3, 4
	s_load_dwordx2 s[2:3], s[0:1], 0x58
	s_waitcnt lgkmcnt(0)
; __global__ void __launch_bounds__(512, 2) mega_fwd(Args a) {
;     ...
; #pragma unroll 1
;     for (int l = 0; l < DEPTH; ++l) {
;         const float* modl = mod + (size_t)l * 4 * NMOD;
;         unsigned char* wl = ws + WS_W + (size_t)l * W_LAYER;
;         const float* xin = l == 0 ? x_in : xout;
	v_writelane_b32 v254, s2, 5
	s_nop 1
	v_writelane_b32 v254, s3, 6
	v_writelane_b32 v254, s8, 7
	s_mov_b32 s2, s79
	s_nop 0
	v_writelane_b32 v254, s9, 8
	v_writelane_b32 v254, s10, 9
	v_writelane_b32 v254, s11, 10
	v_writelane_b32 v254, s12, 11
	v_writelane_b32 v254, s13, 12
	v_writelane_b32 v254, s14, 13
	v_writelane_b32 v254, s15, 14
	s_load_dwordx8 s[8:15], s[0:1], 0x68
	s_waitcnt lgkmcnt(0)
	v_writelane_b32 v254, s8, 15
	s_nop 1
	v_writelane_b32 v254, s9, 16
	v_writelane_b32 v254, s10, 17
	v_writelane_b32 v254, s11, 18
	v_writelane_b32 v254, s12, 19
	v_writelane_b32 v254, s13, 20
	v_writelane_b32 v254, s14, 21
	v_writelane_b32 v254, s15, 22
	v_writelane_b32 v254, s54, 23
	s_nop 1
	v_writelane_b32 v254, s55, 24
	v_writelane_b32 v254, s56, 25
	s_nop 1
	v_writelane_b32 v254, s57, 26
	v_writelane_b32 v254, s58, 27
	s_nop 1
	v_writelane_b32 v254, s59, 28
	v_writelane_b32 v254, s60, 29
	s_nop 1
	v_writelane_b32 v254, s61, 30
	v_writelane_b32 v254, s53, 31
	v_writelane_b32 v254, s80, 32
	s_nop 1
	v_writelane_b32 v254, s81, 33
	v_writelane_b32 v254, s82, 34
	s_nop 1
	v_writelane_b32 v254, s83, 35
	v_writelane_b32 v254, s84, 36
	s_nop 1
	v_writelane_b32 v254, s85, 37
	v_writelane_b32 v254, s86, 38
	s_nop 1
	v_writelane_b32 v254, s87, 39
	v_writelane_b32 v254, s92, 40
	s_nop 1
	v_writelane_b32 v254, s93, 41
	v_writelane_b32 v254, s94, 42
	s_nop 1
	v_writelane_b32 v254, s95, 43
	v_writelane_b32 v254, s96, 44
	s_nop 1
	v_writelane_b32 v254, s97, 45
	v_writelane_b32 v254, s66, 46
	v_writelane_b32 v254, s62, 47
	s_nop 1
	v_writelane_b32 v254, s63, 48
	v_writelane_b32 v254, s64, 49
	s_nop 1
	v_writelane_b32 v254, s65, 50
	v_writelane_b32 v254, s68, 51
	s_nop 1
	v_writelane_b32 v254, s69, 52
	s_branch .LBB0_199

; __device__ __forceinline__ unsigned xb_add(unsigned* p, unsigned v) { return __hip_atomic_fetch_add(p, v, __ATOMIC_RELAXED, __HIP_MEMORY_SCOPE_AGENT); }
; __device__ __forceinline__ void xcd_barrier(const XcdBarrier& b) {
;     ...
;     if (threadIdx.x == 0) {
;         unsigned* bar = b.bar; unsigned bx = b.x; asm volatile("" : "+s"(bx));
;         __builtin_amdgcn_s_waitcnt(0);
;         unsigned nloc = b.st[0], nx = b.st[1];
;         if (nloc == 0u) { xcd_barrier_complete(bar, bx, nloc, nx); b.st[0] = nloc; b.st[1] = nx; }
;         const unsigned old = xb_add(&bar[XB_XSUB(bx)], 1u);
;         const unsigned gen = old / nloc;
;         if (old + 1u == (gen + 1u) * nloc) {
.LBB0_243:
	s_waitcnt vmcnt(0)
	s_barrier
	s_mov_b64 s[0:1], exec
	v_readlane_b32 s2, v252, 3
	v_readlane_b32 s3, v252, 4
	s_and_b64 s[2:3], s[0:1], s[2:3]
	s_mov_b64 exec, s[2:3]
	s_cbranch_execz .LBB0_295
	s_waitcnt vmcnt(0) lgkmcnt(0)
	v_mov_b32_e32 v0, 0x26800
	ds_read_b32 v2, v0
	ds_read_b32 v3, v0 offset:4
	ds_read_b32 v8, v0 offset:8
	v_readlane_b32 s10, v252, 0
	v_readlane_b32 s11, v252, 1
	v_readlane_b32 s12, v252, 2
	s_lshl_b32 s12, s12, 8
	s_add_u32 s14, s10, s12
	s_addc_u32 s15, s11, 0
	s_add_u32 s14, s14, 0x1400
	s_addc_u32 s15, s15, 0
	s_add_u32 s16, s10, 0x3400
	s_addc_u32 s17, s11, 0
	v_mov_b32_e32 v4, 1
	global_atomic_add v5, v161, v4, s[14:15] sc0
	s_waitcnt lgkmcnt(0)
	v_readfirstlane_b32 s18, v2
	v_readfirstlane_b32 s19, v3
	v_cvt_f32_u32_e32 v7, v2
	v_rcp_f32_e32 v7, v7
	s_waitcnt vmcnt(0)
	v_readfirstlane_b32 s13, v5
	v_cvt_f32_u32_e32 v6, v5
	v_mul_f32_e32 v6, v6, v7
	v_cvt_u32_f32_e32 v6, v6
	s_nop 0
	v_readfirstlane_b32 s2, v6
	s_mul_i32 s3, s2, s18
	s_cmp_gt_u32 s3, s13
	s_cbranch_scc0 .Lxb0_a
	s_sub_i32 s2, s2, 1
	s_sub_i32 s3, s3, s18

; __device__ __forceinline__ unsigned xb_ld(unsigned* p)              { return __hip_atomic_load(p, __ATOMIC_RELAXED, __HIP_MEMORY_SCOPE_AGENT); }
; __device__ __forceinline__ unsigned xb_add(unsigned* p, unsigned v) { return __hip_atomic_fetch_add(p, v, __ATOMIC_RELAXED, __HIP_MEMORY_SCOPE_AGENT); }
; #define XB_SPIN(cond, bar) do { unsigned _sp = 0; while (cond) { __builtin_amdgcn_s_sleep(1); \
;     if ((++_sp & 255u) == 0u) { if (xb_ld(&(bar)[XB_TMO])) break; if (_sp > XB_SPIN_CAP) { atomicAdd(&(bar)[XB_TMO], 1u); break; } } } } while (0)
; __device__ __forceinline__ void xcd_barrier(const XcdBarrier& b) {
;     ...
;             const unsigned tg = og / nx;
;             if (og + 1u == (tg + 1u) * nx) xb_add(&bar[XB_TOPGEN], 1u);
;             else XB_SPIN(xb_ld(&bar[XB_TOPGEN]) == tg, bar);
.Lxb0_poll:
	v_readfirstlane_b32 s2, v8
	s_add_i32 s2, s2, 1
	s_mul_i32 s2, s2, s19
	v_add_u32_e32 v8, 1, v8
	ds_write_b32 v0, v8 offset:8
	s_mov_b32 s3, 0

; __device__ __forceinline__ unsigned xb_add(unsigned* p, unsigned v) { return __hip_atomic_fetch_add(p, v, __ATOMIC_RELAXED, __HIP_MEMORY_SCOPE_AGENT); }
; __device__ __forceinline__ void xcd_barrier(const XcdBarrier& b) {
;     ...
;     if (threadIdx.x == 0) {
;         unsigned* bar = b.bar; unsigned bx = b.x; asm volatile("" : "+s"(bx));
;         __builtin_amdgcn_s_waitcnt(0);
;         unsigned nloc = b.st[0], nx = b.st[1];
;         if (nloc == 0u) { xcd_barrier_complete(bar, bx, nloc, nx); b.st[0] = nloc; b.st[1] = nx; }
;         const unsigned old = xb_add(&bar[XB_XSUB(bx)], 1u);
;         const unsigned gen = old / nloc;
;         if (old + 1u == (gen + 1u) * nloc) {
.LBB0_303:
	s_or_b64 exec, exec, s[2:3]
	s_waitcnt vmcnt(0)
	s_waitcnt vmcnt(63) expcnt(7) lgkmcnt(15)
	s_barrier
	s_mov_b64 s[0:1], exec
	v_readlane_b32 s2, v252, 3
	v_readlane_b32 s3, v252, 4
	s_and_b64 s[2:3], s[0:1], s[2:3]
	s_mov_b64 exec, s[2:3]
	s_cbranch_execz .LBB0_355
	s_waitcnt vmcnt(0) lgkmcnt(0)
	v_mov_b32_e32 v0, 0x26800
	ds_read_b32 v2, v0
	ds_read_b32 v3, v0 offset:4
	ds_read_b32 v8, v0 offset:8
	v_readlane_b32 s10, v252, 0
	v_readlane_b32 s11, v252, 1
	v_readlane_b32 s12, v252, 2
	s_lshl_b32 s12, s12, 8
	s_add_u32 s14, s10, s12
	s_addc_u32 s15, s11, 0
	s_add_u32 s14, s14, 0x1400
	s_addc_u32 s15, s15, 0
	s_add_u32 s16, s10, 0x3400
	s_addc_u32 s17, s11, 0
	v_mov_b32_e32 v4, 1
	global_atomic_add v5, v161, v4, s[14:15] sc0
	s_waitcnt lgkmcnt(0)
	v_readfirstlane_b32 s18, v2
	v_readfirstlane_b32 s19, v3
	v_cvt_f32_u32_e32 v7, v2
	v_rcp_f32_e32 v7, v7
	s_waitcnt vmcnt(0)
	v_readfirstlane_b32 s13, v5
	v_cvt_f32_u32_e32 v6, v5
	v_mul_f32_e32 v6, v6, v7
	v_cvt_u32_f32_e32 v6, v6
	s_nop 0
	v_readfirstlane_b32 s2, v6
	s_mul_i32 s3, s2, s18
	s_cmp_gt_u32 s3, s13
	s_cbranch_scc0 .Lxb1_a
	s_sub_i32 s2, s2, 1
	s_sub_i32 s3, s3, s18

; __device__ __forceinline__ unsigned xb_add(unsigned* p, unsigned v) { return __hip_atomic_fetch_add(p, v, __ATOMIC_RELAXED, __HIP_MEMORY_SCOPE_AGENT); }
; __device__ __forceinline__ void xcd_barrier(const XcdBarrier& b) {
;     ...
;     if (threadIdx.x == 0) {
;         unsigned* bar = b.bar; unsigned bx = b.x; asm volatile("" : "+s"(bx));
;         __builtin_amdgcn_s_waitcnt(0);
;         unsigned nloc = b.st[0], nx = b.st[1];
;         if (nloc == 0u) { xcd_barrier_complete(bar, bx, nloc, nx); b.st[0] = nloc; b.st[1] = nx; }
;         const unsigned old = xb_add(&bar[XB_XSUB(bx)], 1u);
;         const unsigned gen = old / nloc;
;         if (old + 1u == (gen + 1u) * nloc) {
.LBB0_482:
	s_or_b64 exec, exec, s[0:1]
	s_waitcnt vmcnt(0)
	s_barrier
	s_mov_b64 s[0:1], exec
	v_readlane_b32 s2, v252, 3
	v_readlane_b32 s3, v252, 4
	s_and_b64 s[2:3], s[0:1], s[2:3]
	s_mov_b64 exec, s[2:3]
	s_cbranch_execz .LBB0_534
	s_waitcnt vmcnt(0) lgkmcnt(0)
	v_mov_b32_e32 v0, 0x26800
	ds_read_b32 v2, v0
	ds_read_b32 v3, v0 offset:4
	ds_read_b32 v8, v0 offset:8
	v_readlane_b32 s10, v252, 0
	v_readlane_b32 s11, v252, 1
	v_readlane_b32 s12, v252, 2
	s_lshl_b32 s12, s12, 8
	s_add_u32 s14, s10, s12
	s_addc_u32 s15, s11, 0
	s_add_u32 s14, s14, 0x1400
	s_addc_u32 s15, s15, 0
	s_add_u32 s16, s10, 0x3400
	s_addc_u32 s17, s11, 0
	v_mov_b32_e32 v4, 1
	global_atomic_add v5, v161, v4, s[14:15] sc0
	s_waitcnt lgkmcnt(0)
	v_readfirstlane_b32 s18, v2
	v_readfirstlane_b32 s19, v3
	v_cvt_f32_u32_e32 v7, v2
	v_rcp_f32_e32 v7, v7
	s_waitcnt vmcnt(0)
	v_readfirstlane_b32 s13, v5
	v_cvt_f32_u32_e32 v6, v5
	v_mul_f32_e32 v6, v6, v7
	v_cvt_u32_f32_e32 v6, v6
	s_nop 0
	v_readfirstlane_b32 s2, v6
	s_mul_i32 s3, s2, s18
	s_cmp_gt_u32 s3, s13
	s_cbranch_scc0 .Lxb2_a
	s_sub_i32 s2, s2, 1
	s_sub_i32 s3, s3, s18

; __device__ __forceinline__ unsigned xb_add(unsigned* p, unsigned v) { return __hip_atomic_fetch_add(p, v, __ATOMIC_RELAXED, __HIP_MEMORY_SCOPE_AGENT); }
; __device__ __forceinline__ void xcd_barrier(const XcdBarrier& b) {
;     ...
;     if (threadIdx.x == 0) {
;         unsigned* bar = b.bar; unsigned bx = b.x; asm volatile("" : "+s"(bx));
;         __builtin_amdgcn_s_waitcnt(0);
;         unsigned nloc = b.st[0], nx = b.st[1];
;         if (nloc == 0u) { xcd_barrier_complete(bar, bx, nloc, nx); b.st[0] = nloc; b.st[1] = nx; }
;         const unsigned old = xb_add(&bar[XB_XSUB(bx)], 1u);
;         const unsigned gen = old / nloc;
;         if (old + 1u == (gen + 1u) * nloc) {
.LBB0_880:
	s_or_b64 exec, exec, s[0:1]
	s_waitcnt vmcnt(0)
	s_barrier
	s_mov_b64 s[0:1], exec
	v_readlane_b32 s2, v252, 3
	v_readlane_b32 s3, v252, 4
	s_and_b64 s[2:3], s[0:1], s[2:3]
	s_mov_b32 s26, 0xbfb8aa3b
	s_mov_b32 s27, 0x800000
	s_mov_b32 s28, 0x3f317217
	s_mov_b32 s29, 0x7f800000
	v_readlane_b32 s20, v254, 55
	v_readlane_b32 s21, v254, 56
	s_mov_b64 exec, s[2:3]
	s_cbranch_execz .LBB0_932
	s_waitcnt vmcnt(0) lgkmcnt(0)
	v_mov_b32_e32 v0, 0x26800
	ds_read_b32 v2, v0
	ds_read_b32 v3, v0 offset:4
	ds_read_b32 v8, v0 offset:8
	v_readlane_b32 s10, v252, 0
	v_readlane_b32 s11, v252, 1
	v_readlane_b32 s12, v252, 2
	s_lshl_b32 s12, s12, 8
	s_add_u32 s14, s10, s12
	s_addc_u32 s15, s11, 0
	s_add_u32 s14, s14, 0x1400
	s_addc_u32 s15, s15, 0
	s_add_u32 s16, s10, 0x3400
	s_addc_u32 s17, s11, 0
	v_mov_b32_e32 v4, 1
	global_atomic_add v5, v161, v4, s[14:15] sc0
	s_waitcnt lgkmcnt(0)
	v_readfirstlane_b32 s18, v2
	v_readfirstlane_b32 s19, v3
	v_cvt_f32_u32_e32 v7, v2
	v_rcp_f32_e32 v7, v7
	s_waitcnt vmcnt(0)
	v_readfirstlane_b32 s13, v5
	v_cvt_f32_u32_e32 v6, v5
	v_mul_f32_e32 v6, v6, v7
	v_cvt_u32_f32_e32 v6, v6
	s_nop 0
	v_readfirstlane_b32 s2, v6
	s_mul_i32 s3, s2, s18
	s_cmp_gt_u32 s3, s13
	s_cbranch_scc0 .Lxb3_a
	s_sub_i32 s2, s2, 1
	s_sub_i32 s3, s3, s18

; __device__ __forceinline__ unsigned xb_add(unsigned* p, unsigned v) { return __hip_atomic_fetch_add(p, v, __ATOMIC_RELAXED, __HIP_MEMORY_SCOPE_AGENT); }
; __device__ __forceinline__ void xcd_barrier(const XcdBarrier& b) {
;     ...
;     if (threadIdx.x == 0) {
;         unsigned* bar = b.bar; unsigned bx = b.x; asm volatile("" : "+s"(bx));
;         __builtin_amdgcn_s_waitcnt(0);
;         unsigned nloc = b.st[0], nx = b.st[1];
;         if (nloc == 0u) { xcd_barrier_complete(bar, bx, nloc, nx); b.st[0] = nloc; b.st[1] = nx; }
;         const unsigned old = xb_add(&bar[XB_XSUB(bx)], 1u);
;         const unsigned gen = old / nloc;
;         if (old + 1u == (gen + 1u) * nloc) {
.LBB0_1070:
	s_waitcnt vmcnt(0)
	s_waitcnt lgkmcnt(0)
	s_barrier
	s_mov_b64 s[0:1], exec
	v_readlane_b32 s2, v252, 3
	v_readlane_b32 s3, v252, 4
	s_and_b64 s[2:3], s[0:1], s[2:3]
	s_mov_b64 s[30:31], 0x2000
	s_mov_b64 exec, s[2:3]
	s_cbranch_execz .LBB0_1122
	s_waitcnt vmcnt(0) lgkmcnt(0)
	v_mov_b32_e32 v0, 0x26800
	ds_read_b32 v2, v0
	ds_read_b32 v3, v0 offset:4
	ds_read_b32 v8, v0 offset:8
	v_readlane_b32 s10, v252, 0
	v_readlane_b32 s11, v252, 1
	v_readlane_b32 s12, v252, 2
	s_lshl_b32 s12, s12, 8
	s_add_u32 s14, s10, s12
	s_addc_u32 s15, s11, 0
	s_add_u32 s14, s14, 0x1400
	s_addc_u32 s15, s15, 0
	s_add_u32 s16, s10, 0x3400
	s_addc_u32 s17, s11, 0
	v_mov_b32_e32 v4, 1
	global_atomic_add v5, v161, v4, s[14:15] sc0
	s_waitcnt lgkmcnt(0)
	v_readfirstlane_b32 s18, v2
	v_readfirstlane_b32 s19, v3
	v_cvt_f32_u32_e32 v7, v2
	v_rcp_f32_e32 v7, v7
	s_waitcnt vmcnt(0)
	v_readfirstlane_b32 s13, v5
	v_cvt_f32_u32_e32 v6, v5
	v_mul_f32_e32 v6, v6, v7
	v_cvt_u32_f32_e32 v6, v6
	s_nop 0
	v_readfirstlane_b32 s2, v6
	s_mul_i32 s3, s2, s18
	s_cmp_gt_u32 s3, s13
	s_cbranch_scc0 .Lxb4_a
	s_sub_i32 s2, s2, 1
	s_sub_i32 s3, s3, s18

; __device__ __forceinline__ unsigned xb_add(unsigned* p, unsigned v) { return __hip_atomic_fetch_add(p, v, __ATOMIC_RELAXED, __HIP_MEMORY_SCOPE_AGENT); }
; __device__ __forceinline__ void xcd_barrier(const XcdBarrier& b) {
;     ...
;     if (threadIdx.x == 0) {
;         unsigned* bar = b.bar; unsigned bx = b.x; asm volatile("" : "+s"(bx));
;         __builtin_amdgcn_s_waitcnt(0);
;         unsigned nloc = b.st[0], nx = b.st[1];
;         if (nloc == 0u) { xcd_barrier_complete(bar, bx, nloc, nx); b.st[0] = nloc; b.st[1] = nx; }
;         const unsigned old = xb_add(&bar[XB_XSUB(bx)], 1u);
;         const unsigned gen = old / nloc;
;         if (old + 1u == (gen + 1u) * nloc) {
.LBB0_1352:
	s_waitcnt vmcnt(0) lgkmcnt(0)
	v_mov_b32_e32 v0, 0x26800
	ds_read_b32 v2, v0
	ds_read_b32 v3, v0 offset:4
	ds_read_b32 v8, v0 offset:8
	v_readlane_b32 s10, v252, 0
	v_readlane_b32 s11, v252, 1
	v_readlane_b32 s12, v252, 2
	s_lshl_b32 s12, s12, 8
	s_add_u32 s14, s10, s12
	s_addc_u32 s15, s11, 0
	s_add_u32 s14, s14, 0x1400
	s_addc_u32 s15, s15, 0
	s_add_u32 s16, s10, 0x3400
	s_addc_u32 s17, s11, 0
	v_mov_b32_e32 v4, 1
	global_atomic_add v5, v161, v4, s[14:15] sc0
	s_waitcnt lgkmcnt(0)
	v_readfirstlane_b32 s18, v2
	v_readfirstlane_b32 s19, v3
	v_cvt_f32_u32_e32 v7, v2
	v_rcp_f32_e32 v7, v7
	s_waitcnt vmcnt(0)
	v_readfirstlane_b32 s13, v5
	v_cvt_f32_u32_e32 v6, v5
	v_mul_f32_e32 v6, v6, v7
	v_cvt_u32_f32_e32 v6, v6
	s_nop 0
	v_readfirstlane_b32 s2, v6
	s_mul_i32 s3, s2, s18
	s_cmp_gt_u32 s3, s13
	s_cbranch_scc0 .Lxb6_a
	s_sub_i32 s2, s2, 1
	s_sub_i32 s3, s3, s18
